# v50: weight copies of layers 1..3 moved out of the prep phase into the 64 tile-less workgroups of each layer's out-projection (hand-written 64x32 block transposer, 32 loads in flight); prep-phase cach
# speedup vs baseline: 1.7957x; 1.0291x over previous
.LBB0_9:
	s_waitcnt lgkmcnt(0)
	s_cmpk_eq_i32 s3, 0x100
	s_cselect_b64 s[4:5], -1, 0
	s_cmpk_lg_i32 s3, 0x100
	v_lshl_add_u32 v1, s59, 3, v6
	v_writelane_b32 v255, s4, 18
	s_cselect_b64 s[38:39], -1, 0
	s_and_b64 vcc, exec, s[38:39]
	v_writelane_b32 v255, s5, 19
	v_mov_b32_e32 v4, v1
	v_mov_b32_e32 v90, v1
	s_cbranch_vccnz .LBB0_14
	s_and_b64 vcc, exec, s[8:9]
	s_cbranch_vccz .LBB0_12
	v_mov_b32_e32 v4, 0xfffff400
	v_mov_b32_e32 v5, -1
	v_mad_u64_u32 v[4:5], s[4:5], v1, 6, v[4:5]
	s_cbranch_execz .LBB0_13
	s_branch .LBB0_14

.LBB0_17:
	s_load_dwordx8 s[8:15], s[0:1], 0x80
	s_andn2_b64 vcc, exec, s[4:5]
	s_mov_b32 s2, s28
	s_waitcnt lgkmcnt(0)
	v_writelane_b32 v255, s8, 20
	s_nop 1
	v_writelane_b32 v255, s9, 21
	v_writelane_b32 v255, s10, 22
	v_writelane_b32 v255, s11, 23
	v_writelane_b32 v255, s12, 24
	v_writelane_b32 v255, s13, 25
	v_writelane_b32 v255, s14, 26
	v_writelane_b32 v255, s15, 27
	s_cbranch_vccnz .LBB0_19
	v_cmp_lt_u32_e32 vcc, 0x6ff, v90
	s_nop 1
	v_cndmask_b32_e64 v5, 1, 2, vcc
	s_mov_b32 s2, 1

.LBB0_22:
	s_lshl_b32 s8, s10, 8
	v_add_u32_e32 v3, s8, v90
	v_mul_hi_i32 v8, v3, s12
	v_lshrrev_b32_e32 v13, 31, v8
	v_ashrrev_i32_e32 v8, 9, v8
	v_add_u32_e32 v18, v8, v13
	v_mul_i32_i24_e32 v8, 0x900, v18
	v_sub_u32_e32 v3, v3, v8
	v_cmp_lt_i32_e32 vcc, s13, v3
	v_ashrrev_i32_e32 v19, 31, v18
	s_and_saveexec_b64 s[8:9], vcc
	s_xor_b64 s[8:9], exec, s[8:9]
	s_cbranch_execz .LBB0_26
	v_readlane_b32 s40, v255, 0
	v_lshl_add_u32 v8, v3, 1, v27
	v_lshlrev_b32_e32 v3, 5, v3
	v_lshlrev_b64 v[16:17], 20, v[18:19]
	v_lshlrev_b64 v[18:19], 22, v[18:19]
	v_readlane_b32 s48, v255, 8
	v_readlane_b32 s49, v255, 9
	v_and_b32_e32 v21, 0x3e0, v3
	v_and_b32_e32 v15, 0x1ffc0, v8
	v_lshl_add_u64 v[18:19], s[48:49], 0, v[18:19]
	v_lshlrev_b32_e32 v8, 2, v21
	v_lshl_add_u64 v[18:19], v[18:19], 0, v[8:9]
	v_mov_b32_e32 v13, v9
	s_mov_b32 s16, 1
	v_lshl_add_u64 v[18:19], v[18:19], 0, v[12:13]
	v_or_b32_e32 v3, v1, v15
	v_or_b32_e32 v20, v6, v15
	s_mov_b32 s17, 0
	s_mov_b32 s18, 32
	v_readlane_b32 s41, v255, 1
	v_readlane_b32 s42, v255, 2
	v_readlane_b32 s43, v255, 3
	v_readlane_b32 s44, v255, 4
	v_readlane_b32 s45, v255, 5
	v_readlane_b32 s46, v255, 6
	v_readlane_b32 s47, v255, 7
	v_readlane_b32 s50, v255, 10
	v_readlane_b32 s51, v255, 11
	v_readlane_b32 s52, v255, 12
	v_readlane_b32 s53, v255, 13
	v_readlane_b32 s54, v255, 14
	v_readlane_b32 s55, v255, 15

.LBB0_30:
	s_or_b64 exec, exec, s[0:1]
	v_lshl_add_u32 v1, s59, 9, v174
	v_add_u32_e32 v1, 0xfffe8000, v1
	s_mov_b32 s0, 0x10000
	s_mov_b32 s2, 0x8000
	v_cmp_gt_u32_e32 vcc, s0, v1
	s_and_saveexec_b64 s[0:1], vcc
	s_cbranch_execz .LBB0_35
	s_add_u32 s4, s56, 0xe200000
	s_addc_u32 s5, s57, 0
	v_lshlrev_b32_e32 v3, 3, v1
	s_mov_b32 s8, 0x40000
	s_mov_b64 s[6:7], 0
	v_mov_b32_e32 v5, 0
	s_mov_b32 s9, 0xffff
	v_mov_b32_e32 v6, v1

.LBB0_35:
	s_or_b64 exec, exec, s[0:1]
	v_lshl_add_u32 v1, s59, 9, v174
	s_lshl_b32 s2, s3, 9
	s_mov_b32 s0, 0x20000
	v_cmp_gt_i32_e32 vcc, s0, v1
	s_and_saveexec_b64 s[0:1], vcc
	s_cbranch_execz .LBB0_40
	s_add_u32 s4, s56, 0xe400000
	s_addc_u32 s5, s57, 0
	v_lshl_add_u32 v3, s59, 12, v11
	s_lshl_b32 s8, s3, 12
	s_mov_b64 s[6:7], 0
	v_mov_b32_e32 v5, 0
	s_mov_b32 s9, 0x1ffff
	v_mov_b32_e32 v6, v1

.LBB0_259:
	s_andn2_b64 vcc, exec, s[4:5]
	s_cbranch_vccz .Lop_active
	s_cmp_gt_u32 s34, 2
	s_cbranch_scc1 .LBB0_307
	v_readfirstlane_b32 s20, v174
	s_add_i32 s21, s59, 0xffffff40
	s_lshr_b32 s20, s20, 6
	s_lshl_b32 s21, s21, 3
	s_add_i32 s21, s21, s20
	s_add_i32 s22, s34, 1
	v_and_b32_e32 v2, 63, v174
	v_and_b32_e32 v3, 31, v2
	v_lshrrev_b32_e32 v4, 5, v2
	s_mul_i32 s23, s20, 0x2100
	s_addk_i32 s23, 0x5000
	v_mul_u32_u24_e32 v5, 33, v4
	v_add_u32_e32 v5, v5, v3
	v_lshl_add_u32 v5, v5, 2, s23
	v_and_b32_e32 v6, 7, v2
	v_lshrrev_b32_e32 v7, 3, v2
	v_mul_u32_u24_e32 v8, 0x108, v6
	v_add_u32_e32 v8, v8, v7
	v_lshl_add_u32 v8, v8, 2, s23
	v_lshlrev_b32_e32 v9, 11, v7
	v_lshl_add_u32 v9, v6, 4, v9
	s_mov_b32 s30, 0
.Ldt_item:
	s_lshl_b32 s35, s30, 9
	s_add_i32 s35, s35, s21
	s_cmpk_ge_u32 s35, 0x900
	s_cbranch_scc1 .Ldt_done
	s_cmpk_ge_u32 s35, 0x700
	s_cbranch_scc1 .Ldt_wout
	s_mul_i32 s36, s35, 0x2493
	s_lshr_b32 s36, s36, 20
	s_mul_i32 s37, s36, 0x70
	s_sub_i32 s37, s35, s37
	s_movk_i32 s41, 0xe00
	v_readlane_b32 s44, v255, 6
	v_readlane_b32 s45, v255, 7
	s_mul_i32 s46, s22, 0xe00000
	s_mul_i32 s48, s22, 0x700000
	s_branch .Ldt_go
.Ldt_wout:
	s_sub_i32 s35, s35, 0x700
	s_lshr_b32 s36, s35, 5
	s_and_b32 s37, s35, 31
	s_movk_i32 s41, 0x400
	v_readlane_b32 s44, v255, 8
	v_readlane_b32 s45, v255, 9
	s_lshl_b32 s46, s22, 22
	s_lshl_b32 s48, s22, 21
	s_add_u32 s48, s48, 0x1c00000
.Ldt_go:
	s_add_u32 s48, s56, s48
	s_addc_u32 s49, s57, 0
	s_add_u32 s44, s44, s46
	s_addc_u32 s45, s45, 0
	s_lshl_b32 s50, s36, 6
	s_mul_i32 s51, s50, s41
	s_lshl_b32 s53, s37, 5
	s_add_i32 s51, s51, s53
	s_lshl_b32 s51, s51, 2
	s_add_u32 s44, s44, s51
	s_addc_u32 s45, s45, 0
	v_mul_lo_u32 v10, v4, s41
	v_add_u32_e32 v10, v10, v3
	v_lshlrev_b32_e32 v10, 2, v10
	s_lshl_b32 s54, s41, 3
	global_load_dword v32, v10, s[44:45]
	s_add_u32 s44, s44, s54
	s_addc_u32 s45, s45, 0
	global_load_dword v33, v10, s[44:45]
	s_add_u32 s44, s44, s54
	s_addc_u32 s45, s45, 0
	global_load_dword v34, v10, s[44:45]
	s_add_u32 s44, s44, s54
	s_addc_u32 s45, s45, 0
	global_load_dword v35, v10, s[44:45]
	s_add_u32 s44, s44, s54
	s_addc_u32 s45, s45, 0
	global_load_dword v36, v10, s[44:45]
	s_add_u32 s44, s44, s54
	s_addc_u32 s45, s45, 0
	global_load_dword v37, v10, s[44:45]
	s_add_u32 s44, s44, s54
	s_addc_u32 s45, s45, 0
	global_load_dword v38, v10, s[44:45]
	s_add_u32 s44, s44, s54
	s_addc_u32 s45, s45, 0
	global_load_dword v39, v10, s[44:45]
	s_add_u32 s44, s44, s54
	s_addc_u32 s45, s45, 0
	global_load_dword v40, v10, s[44:45]
	s_add_u32 s44, s44, s54
	s_addc_u32 s45, s45, 0
	global_load_dword v41, v10, s[44:45]
	s_add_u32 s44, s44, s54
	s_addc_u32 s45, s45, 0
	global_load_dword v42, v10, s[44:45]
	s_add_u32 s44, s44, s54
	s_addc_u32 s45, s45, 0
	global_load_dword v43, v10, s[44:45]
	s_add_u32 s44, s44, s54
	s_addc_u32 s45, s45, 0
	global_load_dword v44, v10, s[44:45]
	s_add_u32 s44, s44, s54
	s_addc_u32 s45, s45, 0
	global_load_dword v45, v10, s[44:45]
	s_add_u32 s44, s44, s54
	s_addc_u32 s45, s45, 0
	global_load_dword v46, v10, s[44:45]
	s_add_u32 s44, s44, s54
	s_addc_u32 s45, s45, 0
	global_load_dword v47, v10, s[44:45]
	s_add_u32 s44, s44, s54
	s_addc_u32 s45, s45, 0
	global_load_dword v48, v10, s[44:45]
	s_add_u32 s44, s44, s54
	s_addc_u32 s45, s45, 0
	global_load_dword v49, v10, s[44:45]
	s_add_u32 s44, s44, s54
	s_addc_u32 s45, s45, 0
	global_load_dword v50, v10, s[44:45]
	s_add_u32 s44, s44, s54
	s_addc_u32 s45, s45, 0
	global_load_dword v51, v10, s[44:45]
	s_add_u32 s44, s44, s54
	s_addc_u32 s45, s45, 0
	global_load_dword v52, v10, s[44:45]
	s_add_u32 s44, s44, s54
	s_addc_u32 s45, s45, 0
	global_load_dword v53, v10, s[44:45]
	s_add_u32 s44, s44, s54
	s_addc_u32 s45, s45, 0
	global_load_dword v54, v10, s[44:45]
	s_add_u32 s44, s44, s54
	s_addc_u32 s45, s45, 0
	global_load_dword v55, v10, s[44:45]
	s_add_u32 s44, s44, s54
	s_addc_u32 s45, s45, 0
	global_load_dword v56, v10, s[44:45]
	s_add_u32 s44, s44, s54
	s_addc_u32 s45, s45, 0
	global_load_dword v57, v10, s[44:45]
	s_add_u32 s44, s44, s54
	s_addc_u32 s45, s45, 0
	global_load_dword v58, v10, s[44:45]
	s_add_u32 s44, s44, s54
	s_addc_u32 s45, s45, 0
	global_load_dword v59, v10, s[44:45]
	s_add_u32 s44, s44, s54
	s_addc_u32 s45, s45, 0
	global_load_dword v60, v10, s[44:45]
	s_add_u32 s44, s44, s54
	s_addc_u32 s45, s45, 0
	global_load_dword v61, v10, s[44:45]
	s_add_u32 s44, s44, s54
	s_addc_u32 s45, s45, 0
	global_load_dword v62, v10, s[44:45]
	s_add_u32 s44, s44, s54
	s_addc_u32 s45, s45, 0
	global_load_dword v63, v10, s[44:45]
	s_add_u32 s44, s44, s54
	s_addc_u32 s45, s45, 0
	s_lshl_b32 s53, s53, 10
	s_add_i32 s53, s53, s50
	s_lshl_b32 s53, s53, 1
	s_add_u32 s48, s48, s53
	s_addc_u32 s49, s49, 0
	s_waitcnt vmcnt(31)
	ds_write_b32 v5, v32
	s_waitcnt vmcnt(30)
	ds_write_b32 v5, v33 offset:264
	s_waitcnt vmcnt(29)
	ds_write_b32 v5, v34 offset:528
	s_waitcnt vmcnt(28)
	ds_write_b32 v5, v35 offset:792
	s_waitcnt vmcnt(27)
	ds_write_b32 v5, v36 offset:1056
	s_waitcnt vmcnt(26)
	ds_write_b32 v5, v37 offset:1320
	s_waitcnt vmcnt(25)
	ds_write_b32 v5, v38 offset:1584
	s_waitcnt vmcnt(24)
	ds_write_b32 v5, v39 offset:1848
	s_waitcnt vmcnt(23)
	ds_write_b32 v5, v40 offset:2112
	s_waitcnt vmcnt(22)
	ds_write_b32 v5, v41 offset:2376
	s_waitcnt vmcnt(21)
	ds_write_b32 v5, v42 offset:2640
	s_waitcnt vmcnt(20)
	ds_write_b32 v5, v43 offset:2904
	s_waitcnt vmcnt(19)
	ds_write_b32 v5, v44 offset:3168
	s_waitcnt vmcnt(18)
	ds_write_b32 v5, v45 offset:3432
	s_waitcnt vmcnt(17)
	ds_write_b32 v5, v46 offset:3696
	s_waitcnt vmcnt(16)
	ds_write_b32 v5, v47 offset:3960
	s_waitcnt vmcnt(15)
	ds_write_b32 v5, v48 offset:4224
	s_waitcnt vmcnt(14)
	ds_write_b32 v5, v49 offset:4488
	s_waitcnt vmcnt(13)
	ds_write_b32 v5, v50 offset:4752
	s_waitcnt vmcnt(12)
	ds_write_b32 v5, v51 offset:5016
	s_waitcnt vmcnt(11)
	ds_write_b32 v5, v52 offset:5280
	s_waitcnt vmcnt(10)
	ds_write_b32 v5, v53 offset:5544
	s_waitcnt vmcnt(9)
	ds_write_b32 v5, v54 offset:5808
	s_waitcnt vmcnt(8)
	ds_write_b32 v5, v55 offset:6072
	s_waitcnt vmcnt(7)
	ds_write_b32 v5, v56 offset:6336
	s_waitcnt vmcnt(6)
	ds_write_b32 v5, v57 offset:6600
	s_waitcnt vmcnt(5)
	ds_write_b32 v5, v58 offset:6864
	s_waitcnt vmcnt(4)
	ds_write_b32 v5, v59 offset:7128
	s_waitcnt vmcnt(3)
	ds_write_b32 v5, v60 offset:7392
	s_waitcnt vmcnt(2)
	ds_write_b32 v5, v61 offset:7656
	s_waitcnt vmcnt(1)
	ds_write_b32 v5, v62 offset:7920
	s_waitcnt vmcnt(0)
	ds_write_b32 v5, v63 offset:8184
	s_waitcnt lgkmcnt(0)
	ds_read2_b32 v[64:65], v8 offset0:0 offset1:33
	ds_read2_b32 v[66:67], v8 offset0:66 offset1:99
	ds_read2_b32 v[68:69], v8 offset0:132 offset1:165
	ds_read2_b32 v[70:71], v8 offset0:198 offset1:231
	s_waitcnt lgkmcnt(0)
	v_cvt_pk_bf16_f32 v72, v64, v65
	v_cvt_pk_bf16_f32 v73, v66, v67
	v_cvt_pk_bf16_f32 v74, v68, v69
	v_cvt_pk_bf16_f32 v75, v70, v71
	global_store_dwordx4 v9, v[72:75], s[48:49]
	s_add_u32 s48, s48, 0x4000
	s_addc_u32 s49, s49, 0
	ds_read2_b32 v[64:65], v8 offset0:8 offset1:41
	ds_read2_b32 v[66:67], v8 offset0:74 offset1:107
	ds_read2_b32 v[68:69], v8 offset0:140 offset1:173
	ds_read2_b32 v[70:71], v8 offset0:206 offset1:239
	s_waitcnt lgkmcnt(0)
	v_cvt_pk_bf16_f32 v72, v64, v65
	v_cvt_pk_bf16_f32 v73, v66, v67
	v_cvt_pk_bf16_f32 v74, v68, v69
	v_cvt_pk_bf16_f32 v75, v70, v71
	global_store_dwordx4 v9, v[72:75], s[48:49]
	s_add_u32 s48, s48, 0x4000
	s_addc_u32 s49, s49, 0
	ds_read2_b32 v[64:65], v8 offset0:16 offset1:49
	ds_read2_b32 v[66:67], v8 offset0:82 offset1:115
	ds_read2_b32 v[68:69], v8 offset0:148 offset1:181
	ds_read2_b32 v[70:71], v8 offset0:214 offset1:247
	s_waitcnt lgkmcnt(0)
	v_cvt_pk_bf16_f32 v72, v64, v65
	v_cvt_pk_bf16_f32 v73, v66, v67
	v_cvt_pk_bf16_f32 v74, v68, v69
	v_cvt_pk_bf16_f32 v75, v70, v71
	global_store_dwordx4 v9, v[72:75], s[48:49]
	s_add_u32 s48, s48, 0x4000
	s_addc_u32 s49, s49, 0
	ds_read2_b32 v[64:65], v8 offset0:24 offset1:57
	ds_read2_b32 v[66:67], v8 offset0:90 offset1:123
	ds_read2_b32 v[68:69], v8 offset0:156 offset1:189
	ds_read2_b32 v[70:71], v8 offset0:222 offset1:255
	s_waitcnt lgkmcnt(0)
	v_cvt_pk_bf16_f32 v72, v64, v65
	v_cvt_pk_bf16_f32 v73, v66, v67
	v_cvt_pk_bf16_f32 v74, v68, v69
	v_cvt_pk_bf16_f32 v75, v70, v71
	global_store_dwordx4 v9, v[72:75], s[48:49]
	s_add_u32 s48, s48, 0x4000
	s_addc_u32 s49, s49, 0
	s_add_i32 s30, s30, 1
	s_branch .Ldt_item

.Lop_active:
	v_bfe_i32 v3, v13, 27, 1
	v_lshlrev_b32_e32 v2, 4, v13
	v_lshrrev_b32_e32 v3, 22, v3
	v_add_u32_e32 v3, v2, v3
	v_and_b32_e32 v3, 0xfffffc00, v3
	v_sub_u32_e32 v3, v2, v3
	v_lshrrev_b32_e32 v4, 4, v3
	v_ashrrev_i32_e32 v0, 31, v13
	v_bitop3_b32 v3, v4, v3, 32 bitop3:0x6c
	v_lshrrev_b32_e32 v0, 26, v0
	v_ashrrev_i32_e32 v5, 31, v3
	v_add_u32_e32 v0, v13, v0
	v_lshrrev_b32_e32 v5, 26, v5
	v_ashrrev_i32_e32 v0, 6, v0
	v_add_u32_e32 v5, v3, v5
	v_lshlrev_b32_e32 v4, 3, v0
	v_ashrrev_i32_e32 v10, 6, v5
	v_and_b32_e32 v5, 0xc0, v5
	v_and_b32_e32 v4, -16, v4
	v_sub_u32_e32 v3, v3, v5
	v_add_u32_e32 v4, v10, v4
	v_ashrrev_i16_sdwa v3, v184, sext(v3) dst_sel:DWORD dst_unused:UNUSED_PAD src0_sel:DWORD src1_sel:BYTE_0
	v_lshlrev_b32_e32 v6, 5, v0
	v_bfe_i32 v11, v3, 0, 16
	v_lshlrev_b32_e32 v3, 1, v4
	v_lshrrev_b32_e32 v5, 2, v4
	v_and_b32_e32 v7, 3, v10
	v_and_b32_e32 v6, 32, v6
	v_and_b32_e32 v3, 24, v3
	v_and_b32_e32 v5, 4, v5
	v_and_or_b32 v7, v4, s96, v7
	v_or3_b32 v3, v7, v5, v3
	v_add_lshl_u32 v5, v6, v11, 1
	v_add_u32_e32 v2, 0x2000, v2
	v_lshl_add_u32 v136, v3, 11, v5
	v_ashrrev_i32_e32 v3, 31, v2
	v_lshrrev_b32_e32 v3, 22, v3
	v_add_u32_e32 v3, v2, v3
	v_ashrrev_i32_e32 v12, 10, v3
	s_lshl_b64 s[4:5], s[34:35], 21
	v_mul_i32_i24_e32 v3, 0x400, v12
	s_add_u32 s1, s72, s4
	v_sub_u32_e32 v2, v2, v3
	s_addc_u32 s2, s73, s5
	v_lshrrev_b32_e32 v3, 4, v2
	s_add_u32 s1, s1, 0x1c00000
	v_bitop3_b32 v2, v3, v2, 32 bitop3:0x6c
	s_addc_u32 s2, s2, 0
	v_lshl_add_u32 v134, v4, 11, v5
	v_ashrrev_i32_e32 v4, 31, v2
	s_ashr_i32 s5, s20, 6
	s_ashr_i32 s4, s20, 8
	v_lshrrev_b32_e32 v4, 26, v4
	s_lshl_b32 s12, s5, 10
	v_add_u32_e32 v4, v2, v4
	s_add_u32 s13, s72, 0x9100000
	v_lshlrev_b32_e32 v3, 3, v12
	v_ashrrev_i32_e32 v14, 6, v4
	v_and_b32_e32 v4, 0xc0, v4
	s_addc_u32 s17, s73, 0
	s_ashr_i32 s7, s6, 31
	s_ashr_i32 s81, s80, 31
	v_and_b32_e32 v3, -16, v3
	v_sub_u32_e32 v2, v2, v4
	s_lshl_b64 s[8:9], s[6:7], 19
	s_lshl_b64 s[10:11], s[80:81], 19
	v_add_u32_e32 v3, v14, v3
	v_ashrrev_i16_sdwa v2, v184, sext(v2) dst_sel:DWORD dst_unused:UNUSED_PAD src0_sel:DWORD src1_sel:BYTE_0
	s_add_u32 s82, s1, s10
	v_lshlrev_b32_e32 v5, 5, v12
	v_bfe_i32 v15, v2, 0, 16
	v_lshlrev_b32_e32 v2, 1, v3
	v_lshrrev_b32_e32 v4, 2, v3
	v_and_b32_e32 v6, 3, v14
	s_addc_u32 s83, s2, s11
	s_add_i32 s30, s12, 0
	v_and_b32_e32 v5, 32, v5
	v_and_b32_e32 v2, 24, v2
	v_and_b32_e32 v4, 4, v4
	v_and_or_b32 v6, v3, s96, v6
	s_add_i32 m0, s30, 0x10000
	v_or3_b32 v2, v6, v4, v2
	v_add_lshl_u32 v4, v5, v15, 1
	global_load_lds_dwordx4 v136, s[82:83]
	s_add_i32 m0, s30, 0x12000
	v_lshl_add_u32 v140, v2, 11, v4
	s_add_u32 s10, s82, 0x40000
	global_load_lds_dwordx4 v140, s[82:83]
	s_addc_u32 s11, s83, 0
	s_add_i32 m0, s30, 0x14000
	v_lshl_add_u32 v138, v3, 11, v4
	global_load_lds_dwordx4 v136, s[10:11]
	s_add_i32 m0, s30, 0x16000
	s_add_u32 s84, s13, s8
	s_addc_u32 s85, s17, s9
	s_add_i32 s35, s30, 0x2000
	global_load_lds_dwordx4 v140, s[10:11]
	s_mov_b32 m0, s30
	s_add_u32 s8, s84, 0x40000
	global_load_lds_dwordx4 v134, s[84:85]
	s_mov_b32 m0, s35
	s_addc_u32 s9, s85, 0
	s_add_i32 s36, s30, 0x4000
	global_load_lds_dwordx4 v138, s[84:85]
	s_mov_b32 m0, s36
	s_add_i32 s37, s30, 0x6000
	global_load_lds_dwordx4 v134, s[8:9]
	s_mov_b32 m0, s37
	v_mov_b32_e32 v137, v1
	global_load_lds_dwordx4 v138, s[8:9]
	v_mov_b32_e32 v141, v1
	v_mov_b32_e32 v135, v1
	v_mov_b32_e32 v139, v1
	s_cmp_eq_u32 s4, 1
	v_lshl_add_u64 v[8:9], s[82:83], 0, v[136:137]
	v_lshl_add_u64 v[6:7], s[82:83], 0, v[140:141]
	v_lshl_add_u64 v[2:3], s[84:85], 0, v[134:135]
	s_cselect_b64 s[8:9], -1, 0
	s_cmp_lg_u32 s4, 1
	v_lshl_add_u64 v[4:5], s[84:85], 0, v[138:139]
	s_cbranch_scc1 .LBB0_262
	s_barrier
